# baseline (speedup 1.0000x reference)
; template <int LSEL>
; __device__ __forceinline__ void hy_conv(const bf16_t* Z, const bf16_t* G, f32x4 (&acc)[4][4], int w, int lane) {
;     ...
;   for (int d = i_lo - (NB - 1); d <= i_hi; ++d) {
;     bf16x8 bf[4][2];
; #pragma unroll
;     for (int k = 0; k < 4; ++k) {
;       int js = (q0 + k) * BPT - d;
;       js = min(max(js, LSEL ? -1 : 0), NB - 1);
;       const bf16_t* bp = Z + zb + 64 * js;
;       bf[k][0] = *(const bf16x8*)bp;
;       bf[k][1] = *(const bf16x8*)(bp + 32);
;     }
;     const bf16_t* gb = G + (L - 64 * d + 8 * quad - r - s);
;     bf16x8 F[6];
; #pragma unroll
;     for (int u = 0; u < 6; ++u) F[u] = hy_afrag(gb + 16 * (u - 3), t2, t1, sh);
; #pragma unroll
;     for (int k = 0; k < 4; ++k) {
;       const int js = (q0 + k) * BPT - d;
;       const bool valid = LSEL ? (js >= -1 && js <= NB - 1) : (js >= 0 && js <= NB - 1);
;       if (valid) {
; #pragma unroll
;         for (int mt = 0; mt < 4; ++mt) {
;           acc[k][mt] = __builtin_amdgcn_mfma_f32_16x16x32_bf16(F[3 - mt], bf[k][0], acc[k][mt], 0, 0, 0);
;           acc[k][mt] = __builtin_amdgcn_mfma_f32_16x16x32_bf16(F[5 - mt], bf[k][1], acc[k][mt], 0, 0, 0);
;         }
;       }
;     }
.LBB0_835:
	v_add_u32_e32 v0, s9, v176
	v_mov_b32_e32 v140, v108
	v_mov_b32_e32 v141, v109
	v_mov_b32_e32 v142, v110
	v_mov_b32_e32 v143, v111
	v_mov_b32_e32 v144, v120
	v_mov_b32_e32 v145, v121
	v_mov_b32_e32 v146, v122
	v_mov_b32_e32 v147, v123
	ds_read2_b32 v[108:109], v0 offset1:1
	ds_read2_b32 v[110:111], v0 offset0:2 offset1:3
	ds_read_b32 v2, v0 offset:16
	ds_read2_b32 v[120:121], v0 offset0:8 offset1:9
	ds_read2_b32 v[122:123], v0 offset0:10 offset1:11
	ds_read_b32 v3, v0 offset:48
	ds_read2_b32 v[124:125], v0 offset0:16 offset1:17
	ds_read2_b32 v[126:127], v0 offset0:18 offset1:19
	ds_read_b32 v177, v0 offset:80
	ds_read2_b32 v[136:137], v0 offset0:24 offset1:25
	ds_read2_b32 v[138:139], v0 offset0:26 offset1:27
	ds_read_b32 v178, v0 offset:112
	s_add_i32 s12, s8, 1
	v_med3_i32 v0, s12, 0, 31
	v_lshl_add_u32 v0, v0, 7, v153
	s_add_i32 s11, s8, 2
	ds_read_b128 v[128:131], v0
	ds_read_b128 v[132:135], v0 offset:64
	s_waitcnt lgkmcnt(11)
	v_alignbit_b32 v108, v109, v108, v152
	v_alignbit_b32 v109, v110, v109, v152
	v_alignbit_b32 v110, v111, v110, v152
	v_alignbit_b32 v111, v2, v111, v152
	v_med3_i32 v0, s11, 0, 31
	s_add_i32 s10, s8, 3
	v_lshl_add_u32 v0, v0, 7, v153
	s_min_u32 s13, s10, 31
	ds_read_b128 v[112:115], v0
	ds_read_b128 v[116:119], v0 offset:64
	s_waitcnt lgkmcnt(10)
	v_alignbit_b32 v120, v121, v120, v152
	v_alignbit_b32 v121, v122, v121, v152
	v_alignbit_b32 v122, v123, v122, v152
	v_alignbit_b32 v123, v3, v123, v152
	v_lshl_add_u32 v0, s13, 7, v153
	ds_read_b128 v[100:103], v0
	ds_read_b128 v[104:107], v0 offset:64
	s_waitcnt lgkmcnt(9)
	v_alignbit_b32 v124, v125, v124, v152
	v_alignbit_b32 v125, v126, v125, v152
	v_alignbit_b32 v126, v127, v126, v152
	v_alignbit_b32 v127, v177, v127, v152
	s_waitcnt lgkmcnt(6)
	v_alignbit_b32 v136, v137, v136, v152
	v_alignbit_b32 v137, v138, v137, v152
	v_alignbit_b32 v138, v139, v138, v152
	v_alignbit_b32 v139, v178, v139, v152
	s_waitcnt lgkmcnt(0)
	s_cmp_lt_u32 s8, 29
	s_cbranch_scc0 .Lhy_slow_835
	v_add_u32_e32 v0, s9, v154
	ds_read_b128 v[166:169], v0
	ds_read_b128 v[170:173], v0 offset:64
	v_mfma_f32_16x16x32_bf16 v[64:67], v[136:139], v[112:115], v[64:67]
	v_mfma_f32_16x16x32_bf16 v[60:63], v[124:127], v[112:115], v[60:63]
	v_mfma_f32_16x16x32_bf16 v[56:59], v[120:123], v[112:115], v[56:59]
	v_mfma_f32_16x16x32_bf16 v[52:55], v[108:111], v[112:115], v[52:55]
	v_mfma_f32_16x16x32_bf16 v[64:67], v[144:147], v[116:119], v[64:67]
	v_mfma_f32_16x16x32_bf16 v[60:63], v[140:143], v[116:119], v[60:63]
	v_mfma_f32_16x16x32_bf16 v[56:59], v[136:139], v[116:119], v[56:59]
	v_mfma_f32_16x16x32_bf16 v[52:55], v[124:127], v[116:119], v[52:55]
	v_mfma_f32_16x16x32_bf16 v[80:83], v[136:139], v[128:131], v[80:83]
	v_mfma_f32_16x16x32_bf16 v[76:79], v[124:127], v[128:131], v[76:79]
	v_mfma_f32_16x16x32_bf16 v[72:75], v[120:123], v[128:131], v[72:75]
	v_mfma_f32_16x16x32_bf16 v[68:71], v[108:111], v[128:131], v[68:71]
	v_mfma_f32_16x16x32_bf16 v[80:83], v[144:147], v[132:135], v[80:83]
	v_mfma_f32_16x16x32_bf16 v[76:79], v[140:143], v[132:135], v[76:79]
	v_mfma_f32_16x16x32_bf16 v[72:75], v[136:139], v[132:135], v[72:75]
	v_mfma_f32_16x16x32_bf16 v[68:71], v[124:127], v[132:135], v[68:71]
	v_mfma_f32_16x16x32_bf16 v[48:51], v[136:139], v[100:103], v[48:51]
	v_mfma_f32_16x16x32_bf16 v[44:47], v[124:127], v[100:103], v[44:47]
	v_mfma_f32_16x16x32_bf16 v[40:43], v[120:123], v[100:103], v[40:43]
	v_mfma_f32_16x16x32_bf16 v[36:39], v[108:111], v[100:103], v[36:39]
	v_mfma_f32_16x16x32_bf16 v[48:51], v[144:147], v[104:107], v[48:51]
	v_mfma_f32_16x16x32_bf16 v[44:47], v[140:143], v[104:107], v[44:47]
	v_mfma_f32_16x16x32_bf16 v[40:43], v[136:139], v[104:107], v[40:43]
	v_mfma_f32_16x16x32_bf16 v[36:39], v[124:127], v[104:107], v[36:39]
	s_waitcnt lgkmcnt(0)
	v_mfma_f32_16x16x32_bf16 v[96:99], v[136:139], v[166:169], v[96:99]
	v_mfma_f32_16x16x32_bf16 v[92:95], v[124:127], v[166:169], v[92:95]
	v_mfma_f32_16x16x32_bf16 v[88:91], v[120:123], v[166:169], v[88:91]
	v_mfma_f32_16x16x32_bf16 v[84:87], v[108:111], v[166:169], v[84:87]
	v_mfma_f32_16x16x32_bf16 v[96:99], v[144:147], v[170:173], v[96:99]
	v_mfma_f32_16x16x32_bf16 v[92:95], v[140:143], v[170:173], v[92:95]
	v_mfma_f32_16x16x32_bf16 v[88:91], v[136:139], v[170:173], v[88:91]
	v_mfma_f32_16x16x32_bf16 v[84:87], v[124:127], v[170:173], v[84:87]
	s_addk_i32 s9, 0xff80
	s_add_i32 s8, s8, -1
	s_cmpk_lg_i32 s9, 0xee80
	s_cbranch_scc1 .LBB0_835
	s_branch .LBB0_843
.Lhy_slow_835:
	s_cmp_gt_u32 s8, 31
	s_cbranch_scc1 .LBB0_839
	v_add_u32_e32 v0, s9, v154
	ds_read_b128 v[166:169], v0
	ds_read_b128 v[170:173], v0 offset:64
	s_waitcnt lgkmcnt(1)
	v_mfma_f32_16x16x32_bf16 v[96:99], v[136:139], v[166:169], v[96:99]
	v_mfma_f32_16x16x32_bf16 v[92:95], v[124:127], v[166:169], v[92:95]
	v_mfma_f32_16x16x32_bf16 v[88:91], v[120:123], v[166:169], v[88:91]
	v_mfma_f32_16x16x32_bf16 v[84:87], v[108:111], v[166:169], v[84:87]
	s_waitcnt lgkmcnt(0)
	v_mfma_f32_16x16x32_bf16 v[96:99], v[144:147], v[170:173], v[96:99]
	v_mfma_f32_16x16x32_bf16 v[92:95], v[140:143], v[170:173], v[92:95]
	v_mfma_f32_16x16x32_bf16 v[88:91], v[136:139], v[170:173], v[88:91]
	v_mfma_f32_16x16x32_bf16 v[84:87], v[124:127], v[170:173], v[84:87]
	s_cmp_gt_u32 s12, 31
	s_cbranch_scc0 .LBB0_840

; template <int LSEL>
; __device__ __forceinline__ void hy_conv(const bf16_t* Z, const bf16_t* G, f32x4 (&acc)[4][4], int w, int lane) {
;     ...
;   for (int d = i_lo - (NB - 1); d <= i_hi; ++d) {
;     bf16x8 bf[4][2];
; #pragma unroll
;     for (int k = 0; k < 4; ++k) {
;       int js = (q0 + k) * BPT - d;
;       js = min(max(js, LSEL ? -1 : 0), NB - 1);
;       const bf16_t* bp = Z + zb + 64 * js;
;       bf[k][0] = *(const bf16x8*)bp;
;       bf[k][1] = *(const bf16x8*)(bp + 32);
;     }
;     const bf16_t* gb = G + (L - 64 * d + 8 * quad - r - s);
;     bf16x8 F[6];
; #pragma unroll
;     for (int u = 0; u < 6; ++u) F[u] = hy_afrag(gb + 16 * (u - 3), t2, t1, sh);
; #pragma unroll
;     for (int k = 0; k < 4; ++k) {
;       const int js = (q0 + k) * BPT - d;
;       const bool valid = LSEL ? (js >= -1 && js <= NB - 1) : (js >= 0 && js <= NB - 1);
;       if (valid) {
; #pragma unroll
;         for (int mt = 0; mt < 4; ++mt) {
;           acc[k][mt] = __builtin_amdgcn_mfma_f32_16x16x32_bf16(F[3 - mt], bf[k][0], acc[k][mt], 0, 0, 0);
;           acc[k][mt] = __builtin_amdgcn_mfma_f32_16x16x32_bf16(F[5 - mt], bf[k][1], acc[k][mt], 0, 0, 0);
;         }
;       }
;     }
.LBB0_928:
	v_add_u32_e32 v0, s8, v176
	v_mov_b32_e32 v140, v108
	v_mov_b32_e32 v141, v109
	v_mov_b32_e32 v142, v110
	v_mov_b32_e32 v143, v111
	v_mov_b32_e32 v144, v120
	v_mov_b32_e32 v145, v121
	v_mov_b32_e32 v146, v122
	v_mov_b32_e32 v147, v123
	ds_read2_b32 v[108:109], v0 offset1:1
	ds_read2_b32 v[110:111], v0 offset0:2 offset1:3
	ds_read_b32 v2, v0 offset:16
	ds_read2_b32 v[120:121], v0 offset0:8 offset1:9
	ds_read2_b32 v[122:123], v0 offset0:10 offset1:11
	ds_read_b32 v3, v0 offset:48
	ds_read2_b32 v[124:125], v0 offset0:16 offset1:17
	ds_read2_b32 v[126:127], v0 offset0:18 offset1:19
	ds_read_b32 v177, v0 offset:80
	ds_read2_b32 v[136:137], v0 offset0:24 offset1:25
	ds_read2_b32 v[138:139], v0 offset0:26 offset1:27
	ds_read_b32 v178, v0 offset:112
	s_add_i32 s12, s9, 1
	v_med3_i32 v0, s12, 0, 31
	v_lshl_add_u32 v0, v0, 7, v153
	s_add_i32 s11, s9, 2
	ds_read_b128 v[128:131], v0
	ds_read_b128 v[132:135], v0 offset:64
	s_waitcnt lgkmcnt(11)
	v_alignbit_b32 v108, v109, v108, v152
	v_alignbit_b32 v109, v110, v109, v152
	v_alignbit_b32 v110, v111, v110, v152
	v_alignbit_b32 v111, v2, v111, v152
	v_med3_i32 v0, s11, 0, 31
	s_add_i32 s10, s9, 3
	v_lshl_add_u32 v0, v0, 7, v153
	s_min_u32 s13, s10, 31
	ds_read_b128 v[112:115], v0
	ds_read_b128 v[116:119], v0 offset:64
	s_waitcnt lgkmcnt(10)
	v_alignbit_b32 v120, v121, v120, v152
	v_alignbit_b32 v121, v122, v121, v152
	v_alignbit_b32 v122, v123, v122, v152
	v_alignbit_b32 v123, v3, v123, v152
	v_lshl_add_u32 v0, s13, 7, v153
	ds_read_b128 v[100:103], v0
	ds_read_b128 v[104:107], v0 offset:64
	s_waitcnt lgkmcnt(9)
	v_alignbit_b32 v124, v125, v124, v152
	v_alignbit_b32 v125, v126, v125, v152
	v_alignbit_b32 v126, v127, v126, v152
	v_alignbit_b32 v127, v177, v127, v152
	s_waitcnt lgkmcnt(6)
	v_alignbit_b32 v136, v137, v136, v152
	v_alignbit_b32 v137, v138, v137, v152
	v_alignbit_b32 v138, v139, v138, v152
	v_alignbit_b32 v139, v178, v139, v152
	s_waitcnt lgkmcnt(0)
	s_cmp_lt_u32 s9, 29
	s_cbranch_scc0 .Lhy_slow_928
	v_add_u32_e32 v0, s8, v154
	ds_read_b128 v[166:169], v0
	ds_read_b128 v[170:173], v0 offset:64
	v_mfma_f32_16x16x32_bf16 v[36:39], v[136:139], v[112:115], v[36:39]
	v_mfma_f32_16x16x32_bf16 v[32:35], v[124:127], v[112:115], v[32:35]
	v_mfma_f32_16x16x32_bf16 v[28:31], v[120:123], v[112:115], v[28:31]
	v_mfma_f32_16x16x32_bf16 v[24:27], v[108:111], v[112:115], v[24:27]
	v_mfma_f32_16x16x32_bf16 v[36:39], v[144:147], v[116:119], v[36:39]
	v_mfma_f32_16x16x32_bf16 v[32:35], v[140:143], v[116:119], v[32:35]
	v_mfma_f32_16x16x32_bf16 v[28:31], v[136:139], v[116:119], v[28:31]
	v_mfma_f32_16x16x32_bf16 v[24:27], v[124:127], v[116:119], v[24:27]
	v_mfma_f32_16x16x32_bf16 v[56:59], v[136:139], v[128:131], v[56:59]
	v_mfma_f32_16x16x32_bf16 v[52:55], v[124:127], v[128:131], v[52:55]
	v_mfma_f32_16x16x32_bf16 v[48:51], v[120:123], v[128:131], v[48:51]
	v_mfma_f32_16x16x32_bf16 v[40:43], v[108:111], v[128:131], v[40:43]
	v_mfma_f32_16x16x32_bf16 v[56:59], v[144:147], v[132:135], v[56:59]
	v_mfma_f32_16x16x32_bf16 v[52:55], v[140:143], v[132:135], v[52:55]
	v_mfma_f32_16x16x32_bf16 v[48:51], v[136:139], v[132:135], v[48:51]
	v_mfma_f32_16x16x32_bf16 v[40:43], v[124:127], v[132:135], v[40:43]
	v_mfma_f32_16x16x32_bf16 v[20:23], v[136:139], v[100:103], v[20:23]
	v_mfma_f32_16x16x32_bf16 v[12:15], v[124:127], v[100:103], v[12:15]
	v_mfma_f32_16x16x32_bf16 v[8:11], v[120:123], v[100:103], v[8:11]
	v_mfma_f32_16x16x32_bf16 v[2:5], v[108:111], v[100:103], v[4:7]
	v_mfma_f32_16x16x32_bf16 v[20:23], v[144:147], v[104:107], v[20:23]
	v_mfma_f32_16x16x32_bf16 v[12:15], v[140:143], v[104:107], v[12:15]
	v_mfma_f32_16x16x32_bf16 v[8:11], v[136:139], v[104:107], v[8:11]
	v_mfma_f32_16x16x32_bf16 v[4:7], v[124:127], v[104:107], v[2:5]
	s_waitcnt lgkmcnt(0)
	v_mfma_f32_16x16x32_bf16 v[76:79], v[136:139], v[166:169], v[76:79]
	v_mfma_f32_16x16x32_bf16 v[68:71], v[124:127], v[166:169], v[68:71]
	v_mfma_f32_16x16x32_bf16 v[64:67], v[120:123], v[166:169], v[64:67]
	v_mfma_f32_16x16x32_bf16 v[60:63], v[108:111], v[166:169], v[60:63]
	v_mfma_f32_16x16x32_bf16 v[76:79], v[144:147], v[170:173], v[76:79]
	v_mfma_f32_16x16x32_bf16 v[68:71], v[140:143], v[170:173], v[68:71]
	v_mfma_f32_16x16x32_bf16 v[64:67], v[136:139], v[170:173], v[64:67]
	v_mfma_f32_16x16x32_bf16 v[60:63], v[124:127], v[170:173], v[60:63]
	s_addk_i32 s8, 0xff80
	s_add_i32 s9, s9, -1
	s_cmpk_lg_i32 s8, 0xee80
	s_cbranch_scc1 .LBB0_928
	s_branch .LBB0_936
.Lhy_slow_928:
	s_cmp_gt_u32 s9, 31
	s_cbranch_scc1 .LBB0_932
	v_add_u32_e32 v0, s8, v154
	ds_read_b128 v[166:169], v0
	ds_read_b128 v[170:173], v0 offset:64
	s_waitcnt lgkmcnt(1)
	v_mfma_f32_16x16x32_bf16 v[76:79], v[136:139], v[166:169], v[76:79]
	v_mfma_f32_16x16x32_bf16 v[68:71], v[124:127], v[166:169], v[68:71]
	v_mfma_f32_16x16x32_bf16 v[64:67], v[120:123], v[166:169], v[64:67]
	v_mfma_f32_16x16x32_bf16 v[60:63], v[108:111], v[166:169], v[60:63]
	s_waitcnt lgkmcnt(0)
	v_mfma_f32_16x16x32_bf16 v[76:79], v[144:147], v[170:173], v[76:79]
	v_mfma_f32_16x16x32_bf16 v[68:71], v[140:143], v[170:173], v[68:71]
	v_mfma_f32_16x16x32_bf16 v[64:67], v[136:139], v[170:173], v[64:67]
	v_mfma_f32_16x16x32_bf16 v[60:63], v[124:127], v[170:173], v[60:63]
	s_cmp_gt_u32 s12, 31
	s_cbranch_scc0 .LBB0_933

; template <int LSEL>
; __device__ __forceinline__ void hy_conv(const bf16_t* Z, const bf16_t* G, f32x4 (&acc)[4][4], int w, int lane) {
;     ...
;   for (int d = i_lo - (NB - 1); d <= i_hi; ++d) {
;     bf16x8 bf[4][2];
; #pragma unroll
;     for (int k = 0; k < 4; ++k) {
;       int js = (q0 + k) * BPT - d;
;       js = min(max(js, LSEL ? -1 : 0), NB - 1);
;       const bf16_t* bp = Z + zb + 64 * js;
;       bf[k][0] = *(const bf16x8*)bp;
;       bf[k][1] = *(const bf16x8*)(bp + 32);
;     }
;     const bf16_t* gb = G + (L - 64 * d + 8 * quad - r - s);
;     bf16x8 F[6];
; #pragma unroll
;     for (int u = 0; u < 6; ++u) F[u] = hy_afrag(gb + 16 * (u - 3), t2, t1, sh);
; #pragma unroll
;     for (int k = 0; k < 4; ++k) {
;       const int js = (q0 + k) * BPT - d;
;       const bool valid = LSEL ? (js >= -1 && js <= NB - 1) : (js >= 0 && js <= NB - 1);
;       if (valid) {
; #pragma unroll
;         for (int mt = 0; mt < 4; ++mt) {
;           acc[k][mt] = __builtin_amdgcn_mfma_f32_16x16x32_bf16(F[3 - mt], bf[k][0], acc[k][mt], 0, 0, 0);
;           acc[k][mt] = __builtin_amdgcn_mfma_f32_16x16x32_bf16(F[5 - mt], bf[k][1], acc[k][mt], 0, 0, 0);
;         }
;       }
;     }
.LBB0_1112:
	v_add_u32_e32 v0, s8, v176
	v_mov_b32_e32 v138, v106
	v_mov_b32_e32 v139, v107
	v_mov_b32_e32 v140, v108
	v_mov_b32_e32 v141, v109
	v_mov_b32_e32 v142, v118
	v_mov_b32_e32 v143, v119
	v_mov_b32_e32 v144, v120
	v_mov_b32_e32 v145, v121
	ds_read2_b32 v[106:107], v0 offset1:1
	ds_read2_b32 v[108:109], v0 offset0:2 offset1:3
	ds_read_b32 v2, v0 offset:16
	ds_read2_b32 v[118:119], v0 offset0:8 offset1:9
	ds_read2_b32 v[120:121], v0 offset0:10 offset1:11
	ds_read_b32 v3, v0 offset:48
	ds_read2_b32 v[122:123], v0 offset0:16 offset1:17
	ds_read2_b32 v[124:125], v0 offset0:18 offset1:19
	ds_read_b32 v177, v0 offset:80
	ds_read2_b32 v[134:135], v0 offset0:24 offset1:25
	ds_read2_b32 v[136:137], v0 offset0:26 offset1:27
	ds_read_b32 v178, v0 offset:112
	s_add_i32 s10, s9, 1
	v_med3_i32 v0, s10, -1, 63
	v_lshl_add_u32 v0, v0, 7, v154
	s_add_i32 s10, s9, 3
	ds_read_b128 v[126:129], v0 offset:128
	ds_read_b128 v[130:133], v0 offset:192
	s_waitcnt lgkmcnt(11)
	v_alignbit_b32 v106, v107, v106, v151
	v_alignbit_b32 v107, v108, v107, v151
	v_alignbit_b32 v108, v109, v108, v151
	v_alignbit_b32 v109, v2, v109, v151
	v_med3_i32 v0, s10, -1, 63
	s_add_i32 s10, s9, 5
	v_lshl_add_u32 v0, v0, 7, v154
	s_min_i32 s10, s10, 63
	ds_read_b128 v[110:113], v0 offset:128
	ds_read_b128 v[114:117], v0 offset:192
	s_waitcnt lgkmcnt(10)
	v_alignbit_b32 v118, v119, v118, v151
	v_alignbit_b32 v119, v120, v119, v151
	v_alignbit_b32 v120, v121, v120, v151
	v_alignbit_b32 v121, v3, v121, v151
	v_lshl_add_u32 v0, s10, 7, v154
	ds_read_b128 v[98:101], v0 offset:128
	ds_read_b128 v[102:105], v0 offset:192
	s_waitcnt lgkmcnt(9)
	v_alignbit_b32 v122, v123, v122, v151
	v_alignbit_b32 v123, v124, v123, v151
	v_alignbit_b32 v124, v125, v124, v151
	v_alignbit_b32 v125, v177, v125, v151
	s_waitcnt lgkmcnt(6)
	v_alignbit_b32 v134, v135, v134, v151
	v_alignbit_b32 v135, v136, v135, v151
	v_alignbit_b32 v136, v137, v136, v151
	v_alignbit_b32 v137, v178, v137, v151
	s_waitcnt lgkmcnt(0)
	s_cmp_lt_u32 s9, 59
	s_cbranch_scc0 .Lhy_slow_1112
	v_add_u32_e32 v0, s8, v155
	ds_read_b128 v[168:171], v0
	ds_read_b128 v[172:175], v0 offset:64
	v_mfma_f32_16x16x32_bf16 v[62:65], v[134:137], v[110:113], v[62:65]
	v_mfma_f32_16x16x32_bf16 v[58:61], v[122:125], v[110:113], v[58:61]
	v_mfma_f32_16x16x32_bf16 v[54:57], v[118:121], v[110:113], v[54:57]
	v_mfma_f32_16x16x32_bf16 v[50:53], v[106:109], v[110:113], v[50:53]
	v_mfma_f32_16x16x32_bf16 v[62:65], v[142:145], v[114:117], v[62:65]
	v_mfma_f32_16x16x32_bf16 v[58:61], v[138:141], v[114:117], v[58:61]
	v_mfma_f32_16x16x32_bf16 v[54:57], v[134:137], v[114:117], v[54:57]
	v_mfma_f32_16x16x32_bf16 v[50:53], v[122:125], v[114:117], v[50:53]
	v_mfma_f32_16x16x32_bf16 v[78:81], v[134:137], v[126:129], v[78:81]
	v_mfma_f32_16x16x32_bf16 v[74:77], v[122:125], v[126:129], v[74:77]
	v_mfma_f32_16x16x32_bf16 v[70:73], v[118:121], v[126:129], v[70:73]
	v_mfma_f32_16x16x32_bf16 v[66:69], v[106:109], v[126:129], v[66:69]
	v_mfma_f32_16x16x32_bf16 v[78:81], v[142:145], v[130:133], v[78:81]
	v_mfma_f32_16x16x32_bf16 v[74:77], v[138:141], v[130:133], v[74:77]
	v_mfma_f32_16x16x32_bf16 v[70:73], v[134:137], v[130:133], v[70:73]
	v_mfma_f32_16x16x32_bf16 v[66:69], v[122:125], v[130:133], v[66:69]
	v_mfma_f32_16x16x32_bf16 v[46:49], v[134:137], v[98:101], v[46:49]
	v_mfma_f32_16x16x32_bf16 v[42:45], v[122:125], v[98:101], v[42:45]
	v_mfma_f32_16x16x32_bf16 v[38:41], v[118:121], v[98:101], v[38:41]
	v_mfma_f32_16x16x32_bf16 v[34:37], v[106:109], v[98:101], v[34:37]
	v_mfma_f32_16x16x32_bf16 v[46:49], v[142:145], v[102:105], v[46:49]
	v_mfma_f32_16x16x32_bf16 v[42:45], v[138:141], v[102:105], v[42:45]
	v_mfma_f32_16x16x32_bf16 v[38:41], v[134:137], v[102:105], v[38:41]
	v_mfma_f32_16x16x32_bf16 v[34:37], v[122:125], v[102:105], v[34:37]
	s_waitcnt lgkmcnt(0)
	v_mfma_f32_16x16x32_bf16 v[94:97], v[134:137], v[168:171], v[94:97]
	v_mfma_f32_16x16x32_bf16 v[90:93], v[122:125], v[168:171], v[90:93]
	v_mfma_f32_16x16x32_bf16 v[86:89], v[118:121], v[168:171], v[86:89]
	v_mfma_f32_16x16x32_bf16 v[82:85], v[106:109], v[168:171], v[82:85]
	v_mfma_f32_16x16x32_bf16 v[94:97], v[142:145], v[172:175], v[94:97]
	v_mfma_f32_16x16x32_bf16 v[90:93], v[138:141], v[172:175], v[90:93]
	v_mfma_f32_16x16x32_bf16 v[86:89], v[134:137], v[172:175], v[86:89]
	v_mfma_f32_16x16x32_bf16 v[82:85], v[122:125], v[172:175], v[82:85]
	s_add_i32 s9, s9, -1
	s_addk_i32 s8, 0xff80
	s_cmpk_lg_i32 s8, 0xdc80
	s_cbranch_scc1 .LBB0_1112
	s_branch .LBB0_1120
.Lhy_slow_1112:
	s_cmp_gt_u32 s9, 64
	s_cbranch_scc1 .LBB0_1116
	v_add_u32_e32 v0, s8, v155
	ds_read_b128 v[168:171], v0
	ds_read_b128 v[172:175], v0 offset:64
	s_waitcnt lgkmcnt(1)
	v_mfma_f32_16x16x32_bf16 v[94:97], v[134:137], v[168:171], v[94:97]
	v_mfma_f32_16x16x32_bf16 v[90:93], v[122:125], v[168:171], v[90:93]
	v_mfma_f32_16x16x32_bf16 v[86:89], v[118:121], v[168:171], v[86:89]
	v_mfma_f32_16x16x32_bf16 v[82:85], v[106:109], v[168:171], v[82:85]
	s_waitcnt lgkmcnt(0)
	v_mfma_f32_16x16x32_bf16 v[94:97], v[142:145], v[172:175], v[94:97]
	v_mfma_f32_16x16x32_bf16 v[90:93], v[138:141], v[172:175], v[90:93]
	v_mfma_f32_16x16x32_bf16 v[86:89], v[134:137], v[172:175], v[86:89]
	v_mfma_f32_16x16x32_bf16 v[82:85], v[122:125], v[172:175], v[82:85]
	s_add_i32 s10, s9, 2
	s_cmp_gt_u32 s10, 64
	s_cbranch_scc0 .LBB0_1117

; template <int LSEL>
; __device__ __forceinline__ void hy_conv(const bf16_t* Z, const bf16_t* G, f32x4 (&acc)[4][4], int w, int lane) {
;     ...
;   for (int d = i_lo - (NB - 1); d <= i_hi; ++d) {
;     bf16x8 bf[4][2];
; #pragma unroll
;     for (int k = 0; k < 4; ++k) {
;       int js = (q0 + k) * BPT - d;
;       js = min(max(js, LSEL ? -1 : 0), NB - 1);
;       const bf16_t* bp = Z + zb + 64 * js;
;       bf[k][0] = *(const bf16x8*)bp;
;       bf[k][1] = *(const bf16x8*)(bp + 32);
;     }
;     const bf16_t* gb = G + (L - 64 * d + 8 * quad - r - s);
;     bf16x8 F[6];
; #pragma unroll
;     for (int u = 0; u < 6; ++u) F[u] = hy_afrag(gb + 16 * (u - 3), t2, t1, sh);
; #pragma unroll
;     for (int k = 0; k < 4; ++k) {
;       const int js = (q0 + k) * BPT - d;
;       const bool valid = LSEL ? (js >= -1 && js <= NB - 1) : (js >= 0 && js <= NB - 1);
;       if (valid) {
; #pragma unroll
;         for (int mt = 0; mt < 4; ++mt) {
;           acc[k][mt] = __builtin_amdgcn_mfma_f32_16x16x32_bf16(F[3 - mt], bf[k][0], acc[k][mt], 0, 0, 0);
;           acc[k][mt] = __builtin_amdgcn_mfma_f32_16x16x32_bf16(F[5 - mt], bf[k][1], acc[k][mt], 0, 0, 0);
;         }
;       }
;     }
.LBB0_1205:
	v_add_u32_e32 v0, s9, v176
	v_mov_b32_e32 v138, v106
	v_mov_b32_e32 v139, v107
	v_mov_b32_e32 v140, v108
	v_mov_b32_e32 v141, v109
	v_mov_b32_e32 v142, v118
	v_mov_b32_e32 v143, v119
	v_mov_b32_e32 v144, v120
	v_mov_b32_e32 v145, v121
	ds_read2_b32 v[106:107], v0 offset1:1
	ds_read2_b32 v[108:109], v0 offset0:2 offset1:3
	ds_read_b32 v2, v0 offset:16
	ds_read2_b32 v[118:119], v0 offset0:8 offset1:9
	ds_read2_b32 v[120:121], v0 offset0:10 offset1:11
	ds_read_b32 v3, v0 offset:48
	ds_read2_b32 v[122:123], v0 offset0:16 offset1:17
	ds_read2_b32 v[124:125], v0 offset0:18 offset1:19
	ds_read_b32 v177, v0 offset:80
	ds_read2_b32 v[134:135], v0 offset0:24 offset1:25
	ds_read2_b32 v[136:137], v0 offset0:26 offset1:27
	ds_read_b32 v178, v0 offset:112
	s_add_i32 s10, s8, 1
	v_med3_i32 v0, s10, -1, 63
	v_lshl_add_u32 v0, v0, 7, v154
	s_add_i32 s10, s8, 3
	ds_read_b128 v[126:129], v0 offset:128
	ds_read_b128 v[130:133], v0 offset:192
	s_waitcnt lgkmcnt(11)
	v_alignbit_b32 v106, v107, v106, v151
	v_alignbit_b32 v107, v108, v107, v151
	v_alignbit_b32 v108, v109, v108, v151
	v_alignbit_b32 v109, v2, v109, v151
	v_med3_i32 v0, s10, -1, 63
	s_add_i32 s10, s8, 5
	v_lshl_add_u32 v0, v0, 7, v154
	s_min_i32 s10, s10, 63
	ds_read_b128 v[110:113], v0 offset:128
	ds_read_b128 v[114:117], v0 offset:192
	s_waitcnt lgkmcnt(10)
	v_alignbit_b32 v118, v119, v118, v151
	v_alignbit_b32 v119, v120, v119, v151
	v_alignbit_b32 v120, v121, v120, v151
	v_alignbit_b32 v121, v3, v121, v151
	v_lshl_add_u32 v0, s10, 7, v154
	ds_read_b128 v[98:101], v0 offset:128
	ds_read_b128 v[102:105], v0 offset:192
	s_waitcnt lgkmcnt(9)
	v_alignbit_b32 v122, v123, v122, v151
	v_alignbit_b32 v123, v124, v123, v151
	v_alignbit_b32 v124, v125, v124, v151
	v_alignbit_b32 v125, v177, v125, v151
	s_waitcnt lgkmcnt(6)
	v_alignbit_b32 v134, v135, v134, v151
	v_alignbit_b32 v135, v136, v135, v151
	v_alignbit_b32 v136, v137, v136, v151
	v_alignbit_b32 v137, v178, v137, v151
	s_waitcnt lgkmcnt(0)
	s_cmp_lt_u32 s8, 59
	s_cbranch_scc0 .Lhy_slow_1205
	v_add_u32_e32 v0, s9, v155
	ds_read_b128 v[168:171], v0
	ds_read_b128 v[172:175], v0 offset:64
	v_mfma_f32_16x16x32_bf16 v[34:37], v[134:137], v[110:113], v[34:37]
	v_mfma_f32_16x16x32_bf16 v[30:33], v[122:125], v[110:113], v[30:33]
	v_mfma_f32_16x16x32_bf16 v[26:29], v[118:121], v[110:113], v[26:29]
	v_mfma_f32_16x16x32_bf16 v[22:25], v[106:109], v[110:113], v[22:25]
	v_mfma_f32_16x16x32_bf16 v[34:37], v[142:145], v[114:117], v[34:37]
	v_mfma_f32_16x16x32_bf16 v[30:33], v[138:141], v[114:117], v[30:33]
	v_mfma_f32_16x16x32_bf16 v[26:29], v[134:137], v[114:117], v[26:29]
	v_mfma_f32_16x16x32_bf16 v[22:25], v[122:125], v[114:117], v[22:25]
	v_mfma_f32_16x16x32_bf16 v[54:57], v[134:137], v[126:129], v[54:57]
	v_mfma_f32_16x16x32_bf16 v[50:53], v[122:125], v[126:129], v[50:53]
	v_mfma_f32_16x16x32_bf16 v[46:49], v[118:121], v[126:129], v[46:49]
	v_mfma_f32_16x16x32_bf16 v[38:41], v[106:109], v[126:129], v[38:41]
	v_mfma_f32_16x16x32_bf16 v[54:57], v[142:145], v[130:133], v[54:57]
	v_mfma_f32_16x16x32_bf16 v[50:53], v[138:141], v[130:133], v[50:53]
	v_mfma_f32_16x16x32_bf16 v[46:49], v[134:137], v[130:133], v[46:49]
	v_mfma_f32_16x16x32_bf16 v[38:41], v[122:125], v[130:133], v[38:41]
	v_mfma_f32_16x16x32_bf16 v[18:21], v[134:137], v[98:101], v[18:21]
	v_mfma_f32_16x16x32_bf16 v[14:17], v[122:125], v[98:101], v[14:17]
	v_mfma_f32_16x16x32_bf16 v[10:13], v[118:121], v[98:101], v[10:13]
	v_mfma_f32_16x16x32_bf16 v[6:9], v[106:109], v[98:101], v[6:9]
	v_mfma_f32_16x16x32_bf16 v[18:21], v[142:145], v[102:105], v[18:21]
	v_mfma_f32_16x16x32_bf16 v[14:17], v[138:141], v[102:105], v[14:17]
	v_mfma_f32_16x16x32_bf16 v[10:13], v[134:137], v[102:105], v[10:13]
	v_mfma_f32_16x16x32_bf16 v[6:9], v[122:125], v[102:105], v[6:9]
	s_waitcnt lgkmcnt(0)
	v_mfma_f32_16x16x32_bf16 v[74:77], v[134:137], v[168:171], v[74:77]
	v_mfma_f32_16x16x32_bf16 v[66:69], v[122:125], v[168:171], v[66:69]
	v_mfma_f32_16x16x32_bf16 v[62:65], v[118:121], v[168:171], v[62:65]
	v_mfma_f32_16x16x32_bf16 v[58:61], v[106:109], v[168:171], v[58:61]
	v_mfma_f32_16x16x32_bf16 v[74:77], v[142:145], v[172:175], v[74:77]
	v_mfma_f32_16x16x32_bf16 v[66:69], v[138:141], v[172:175], v[66:69]
	v_mfma_f32_16x16x32_bf16 v[62:65], v[134:137], v[172:175], v[62:65]
	v_mfma_f32_16x16x32_bf16 v[58:61], v[122:125], v[172:175], v[58:61]
	s_add_i32 s8, s8, -1
	s_addk_i32 s9, 0xff80
	s_cmpk_lg_i32 s9, 0xdc80
	s_cbranch_scc1 .LBB0_1205
	s_branch .LBB0_1213
.Lhy_slow_1205:
	s_cmp_gt_u32 s8, 64
	s_cbranch_scc1 .LBB0_1209
	v_add_u32_e32 v0, s9, v155
	ds_read_b128 v[168:171], v0
	ds_read_b128 v[172:175], v0 offset:64
	s_waitcnt lgkmcnt(1)
	v_mfma_f32_16x16x32_bf16 v[74:77], v[134:137], v[168:171], v[74:77]
	v_mfma_f32_16x16x32_bf16 v[66:69], v[122:125], v[168:171], v[66:69]
	v_mfma_f32_16x16x32_bf16 v[62:65], v[118:121], v[168:171], v[62:65]
	v_mfma_f32_16x16x32_bf16 v[58:61], v[106:109], v[168:171], v[58:61]
	s_waitcnt lgkmcnt(0)
	v_mfma_f32_16x16x32_bf16 v[74:77], v[142:145], v[172:175], v[74:77]
	v_mfma_f32_16x16x32_bf16 v[66:69], v[138:141], v[172:175], v[66:69]
	v_mfma_f32_16x16x32_bf16 v[62:65], v[134:137], v[172:175], v[62:65]
	v_mfma_f32_16x16x32_bf16 v[58:61], v[122:125], v[172:175], v[58:61]
	s_add_i32 s10, s8, 2
	s_cmp_gt_u32 s10, 64
	s_cbranch_scc0 .LBB0_1210
